# on v54: pipelined unit entry skips the prologue kmax wait (retired at hand-over); ws pointer reused in the pipelined decode
# baseline (speedup 1.0000x reference)
.Lpipe_nofetch:
	s_add_u32 s2, s78, s8
	s_addc_u32 s3, s79, s9
	v_ashrrev_i32_e32 v173, 31, v172
	v_lshl_add_u64 v[2:3], v[172:173], 2, s[2:3]
	v_mov_b32_e32 v0, v175
	global_load_dwordx4 v[94:97], v[2:3], off
	global_load_dwordx4 v[90:93], v[2:3], off offset:32
	global_load_dwordx4 v[86:89], v[2:3], off offset:64
	global_load_dwordx4 v[82:85], v[2:3], off offset:96
	global_load_dwordx4 v[14:17], v[2:3], off offset:128
	global_load_dwordx4 v[10:13], v[2:3], off offset:160
	global_load_dwordx4 v[6:9], v[2:3], off offset:192
	s_nop 0
	global_load_dwordx4 v[2:5], v[2:3], off offset:224
	v_mov_b32_e32 v147, 0
	s_cmpk_gt_i32 s46, 0x4f
	v_readlane_b32 s2, v245, 13
	s_cselect_b32 s2, s2, 0
	s_sub_i32 s2, s46, s2
	s_bfe_u32 s4, s2, 0x30001
	s_and_b32 s3, s2, 1
	s_xor_b32 s5, s4, 7
	s_or_b32 s4, s4, 8
	s_cmp_eq_u32 s3, 0
	s_cselect_b32 s3, s4, s5
	s_mov_b64 s[4:5], s[0:1]
	s_mov_b64 s[12:13], s[0:1]
	s_mov_b64 s[4:5], s[74:75]
	s_mov_b64 s[12:13], s[0:1]
	s_ashr_i32 s2, s2, 4
	s_sub_i32 s12, 8, s2
	v_cvt_f32_i32_e32 v146, s12
	v_mov_b32_e32 v156, v220
	v_readlane_b32 s13, v245, 17
	v_exp_f32_e64 v146, -v146
	s_sub_i32 s55, 7, s2
	s_lshl_b32 s55, s55, 6
	v_ashrrev_i32_e32 v148, 5, v156
	v_readfirstlane_b32 s12, v146
	v_ashrrev_i32_e32 v146, 3, v156
	v_add_u32_e32 v146, s13, v146
	v_mul_lo_u32 v149, v146, s88
	v_lshrrev_b32_e32 v146, 1, v146
	s_add_i32 s13, s55, 0x200
	v_xor_b32_e32 v146, v146, v156
	v_add_u32_e32 v149, s13, v149
	v_lshlrev_b32_e32 v146, 3, v146
	v_readlane_b32 s13, v245, 16
	v_and_or_b32 v146, v146, 56, v149
	v_lshlrev_b32_e32 v150, 3, v156
	v_lshl_add_u32 v149, v148, 3, s13
	v_readlane_b32 s13, v245, 18
	s_add_i32 s13, s13, s55
	v_and_b32_e32 v157, 24, v150
	v_or_b32_e32 v155, s13, v157
	v_readlane_b32 s13, v245, 19
	s_waitcnt lgkmcnt(0)
	s_add_u32 s4, s4, s13
	s_addc_u32 s5, s5, 0
	s_add_u32 s60, s4, 0x13200000
	s_addc_u32 s61, s5, 0
	s_mul_i32 s4, s3, 0xc0000
	s_add_u32 s80, s60, s4
	v_lshlrev_b32_e32 v146, 1, v146
	s_addc_u32 s81, s61, 0
	s_movk_i32 s4, 0xfc00
	v_lshl_add_u64 v[150:151], s[80:81], 0, v[146:147]
	s_mov_b32 s5, -1
	v_lshl_add_u64 v[152:153], v[150:151], 0, s[4:5]
	v_readlane_b32 s5, v245, 22
	s_mov_b32 s4, m0
	s_mov_b32 m0, s5
	s_nop 0
	global_load_lds_dwordx4 v[152:153], off
	s_mov_b32 m0, s4
	s_mov_b64 s[4:5], 0x2fc00
	v_bfe_u32 v154, v156, 2, 3
	v_lshl_add_u64 v[152:153], v[150:151], 0, s[4:5]
	v_readlane_b32 s5, v245, 20
	s_mov_b32 s4, m0
	s_mov_b32 m0, s5
	s_nop 0
	global_load_lds_dwordx4 v[152:153], off
	s_mov_b32 m0, s4
	s_mov_b64 s[4:5], 0x5fc00
	v_or_b32_e32 v149, v149, v154
	v_lshl_add_u64 v[152:153], v[150:151], 0, s[4:5]
	v_readlane_b32 s5, v245, 21
	s_mov_b32 s4, m0
	s_mov_b32 m0, s5
	s_nop 0
	global_load_lds_dwordx4 v[152:153], off
	s_mov_b32 m0, s4
	s_mov_b64 s[4:5], 0x8fc00
	v_mul_lo_u32 v149, v149, s88
	v_lshl_add_u64 v[152:153], v[150:151], 0, s[4:5]
	v_readlane_b32 s5, v245, 23
	s_mov_b32 s4, m0
	s_mov_b32 m0, s5
	s_nop 0
	global_load_lds_dwordx4 v[152:153], off
	s_mov_b32 m0, s4
	v_add_lshl_u32 v170, v155, v149, 1
	s_mov_b32 s4, m0
	s_mov_b32 m0, s64
	s_nop 0
	global_load_lds_dwordx4 v[150:151], off
	s_mov_b32 m0, s4
	v_mov_b32_e32 v171, v1
	v_lshl_add_u64 v[150:151], s[80:81], 0, v[170:171]
	v_readlane_b32 s5, v245, 24
	s_mov_b32 s4, m0
	s_mov_b32 m0, s5
	s_nop 0
	global_load_lds_dwordx4 v[150:151], off
	s_mov_b32 m0, s4
	v_lshlrev_b32_e32 v150, 2, v156
	v_readlane_b32 s4, v245, 25
	v_and_b32_e32 v155, 4, v150
	v_bitop3_b32 v150, v150, v154, 4 bitop3:0x6c
	v_lshl_add_u32 v149, v156, 6, s4
	v_and_b32_e32 v149, 0xffffff80, v149
	v_add_u32_e32 v149, s63, v149
	v_lshl_add_u32 v150, v150, 4, v149
	s_ashr_i32 s101, s2, 31
	s_mov_b32 s100, s2
	s_lshl_b64 s[100:101], s[100:101], 2
	s_sub_u32 s100, s7, s100
	s_subb_u32 s101, s33, s101
	v_mov_b32_e32 v248, 0
	global_load_dword v249, v248, s[100:101] offset:28 sc1
	s_add_u32 s100, s80, 0x30000
	s_addc_u32 s101, s81, 0
	v_lshl_add_u64 v[250:251], s[100:101], 0, v[146:147]
	v_lshl_add_u64 v[252:253], s[100:101], 0, v[170:171]
	v_readlane_b32 s98, v245, 27
	s_mov_b32 s99, m0
	s_mov_b32 m0, s98
	s_nop 0
	global_load_lds_dwordx4 v[250:251], off
	v_readlane_b32 s98, v245, 28
	s_nop 0
	s_mov_b32 m0, s98
	s_nop 0
	global_load_lds_dwordx4 v[252:253], off
	s_add_u32 s100, s80, 0x60000
	s_addc_u32 s101, s81, 0
	v_lshl_add_u64 v[250:251], s[100:101], 0, v[146:147]
	v_lshl_add_u64 v[252:253], s[100:101], 0, v[170:171]
	v_readlane_b32 s98, v245, 29
	s_nop 0
	s_mov_b32 m0, s98
	s_nop 0
	global_load_lds_dwordx4 v[250:251], off
	v_readlane_b32 s98, v245, 30
	s_nop 0
	s_mov_b32 m0, s98
	s_nop 0
	global_load_lds_dwordx4 v[252:253], off
	s_mov_b32 m0, s99
	s_mov_b32 s4, s2
	s_mov_b32 s5, s3
	s_ashr_i32 s77, s76, 31
	v_permlane32_swap_b32_e32 v175, v0
	s_nop 0
	v_add_f32_e32 v0, v175, v0
	v_div_scale_f32 v98, s[2:3], v0, v0, 1.0
	v_rcp_f32_e32 v99, v98
	s_nop 0
	v_fma_f32 v100, -v98, v99, 1.0
	v_fmac_f32_e32 v99, v100, v99
	v_div_scale_f32 v100, vcc, 1.0, v0, 1.0
	v_mul_f32_e32 v101, v100, v99
	v_fma_f32 v102, -v98, v101, v100
	v_fmac_f32_e32 v101, v102, v99
	v_fma_f32 v98, -v98, v101, v100
	v_div_fmas_f32 v98, v98, v99, v101
	v_div_fixup_f32 v0, v98, v0, 1.0
	v_mov_b32_e32 v98, v174
	s_nop 1
	v_permlane32_swap_b32_e32 v174, v98
	s_nop 0
	v_add_f32_e32 v98, v174, v98
	v_div_scale_f32 v99, s[2:3], v98, v98, 1.0
	v_rcp_f32_e32 v100, v99
	s_mov_b32 s2, 0xf800000
	v_fma_f32 v101, -v99, v100, 1.0
	v_fmac_f32_e32 v100, v101, v100
	v_div_scale_f32 v101, vcc, 1.0, v98, 1.0
	v_mul_f32_e32 v102, v101, v100
	v_fma_f32 v103, -v99, v102, v101
	v_fmac_f32_e32 v102, v103, v100
	v_fma_f32 v99, -v99, v102, v101
	v_div_fmas_f32 v99, v99, v100, v102
	v_div_fixup_f32 v98, v99, v98, 1.0
	v_mul_f32_e32 v98, v183, v98
	v_mul_f32_e32 v66, v66, v98
	v_fma_f32 v50, v50, v0, -v66
	v_mul_f32_e32 v66, v67, v98
	v_fma_f32 v51, v51, v0, -v66
	v_mul_f32_e32 v66, v51, v51
	v_mul_f32_e32 v67, v68, v98
	v_fmac_f32_e32 v66, v50, v50
	v_fma_f32 v52, v52, v0, -v67
	v_mul_f32_e32 v67, v69, v98
	v_fmac_f32_e32 v66, v52, v52
	v_fma_f32 v53, v53, v0, -v67
	v_mul_f32_e32 v67, v70, v98
	v_fmac_f32_e32 v66, v53, v53
	v_fma_f32 v54, v54, v0, -v67
	v_mul_f32_e32 v67, v71, v98
	v_fmac_f32_e32 v66, v54, v54
	v_fma_f32 v55, v55, v0, -v67
	v_mul_f32_e32 v67, v72, v98
	v_fmac_f32_e32 v66, v55, v55
	v_fma_f32 v56, v56, v0, -v67
	v_mul_f32_e32 v67, v73, v98
	v_fmac_f32_e32 v66, v56, v56
	v_fma_f32 v57, v57, v0, -v67
	v_mul_f32_e32 v67, v74, v98
	v_fmac_f32_e32 v66, v57, v57
	v_fma_f32 v58, v58, v0, -v67
	v_mul_f32_e32 v67, v75, v98
	v_fmac_f32_e32 v66, v58, v58
	v_fma_f32 v59, v59, v0, -v67
	v_mul_f32_e32 v67, v76, v98
	v_fmac_f32_e32 v66, v59, v59
	v_fma_f32 v60, v60, v0, -v67
	v_mul_f32_e32 v67, v77, v98
	v_fmac_f32_e32 v66, v60, v60
	v_fma_f32 v61, v61, v0, -v67
	v_mul_f32_e32 v67, v78, v98
	v_fmac_f32_e32 v66, v61, v61
	v_fma_f32 v62, v62, v0, -v67
	v_mul_f32_e32 v67, v79, v98
	v_fmac_f32_e32 v66, v62, v62
	v_fma_f32 v63, v63, v0, -v67
	v_mul_f32_e32 v67, v80, v98
	v_fmac_f32_e32 v66, v63, v63
	v_fma_f32 v64, v64, v0, -v67
	v_mul_f32_e32 v67, v81, v98
	v_fmac_f32_e32 v66, v64, v64
	v_fma_f32 v65, v65, v0, -v67
	v_mul_f32_e32 v34, v34, v98
	v_fmac_f32_e32 v66, v65, v65
	v_fma_f32 v34, v18, v0, -v34
	v_mul_f32_e32 v18, v35, v98
	v_fmac_f32_e32 v66, v34, v34
	v_fma_f32 v35, v19, v0, -v18
	v_mul_f32_e32 v18, v36, v98
	v_fmac_f32_e32 v66, v35, v35
	v_fma_f32 v36, v20, v0, -v18
	v_mul_f32_e32 v18, v37, v98
	v_fmac_f32_e32 v66, v36, v36
	v_fma_f32 v37, v21, v0, -v18
	v_mul_f32_e32 v18, v38, v98
	v_fmac_f32_e32 v66, v37, v37
	v_fma_f32 v38, v22, v0, -v18
	v_mul_f32_e32 v18, v39, v98
	v_fmac_f32_e32 v66, v38, v38
	v_fma_f32 v39, v23, v0, -v18
	v_mul_f32_e32 v18, v40, v98
	v_fmac_f32_e32 v66, v39, v39
	v_fma_f32 v24, v24, v0, -v18
	v_mul_f32_e32 v18, v41, v98
	v_fmac_f32_e32 v66, v24, v24
	v_fma_f32 v25, v25, v0, -v18
	v_mul_f32_e32 v18, v42, v98
	v_fmac_f32_e32 v66, v25, v25
	v_fma_f32 v26, v26, v0, -v18
	v_mul_f32_e32 v18, v43, v98
	v_fmac_f32_e32 v66, v26, v26
	v_fma_f32 v27, v27, v0, -v18
	v_mul_f32_e32 v18, v44, v98
	v_fmac_f32_e32 v66, v27, v27
	v_fma_f32 v28, v28, v0, -v18
	v_mul_f32_e32 v18, v45, v98
	v_fmac_f32_e32 v66, v28, v28
	v_fma_f32 v29, v29, v0, -v18
	v_mul_f32_e32 v18, v46, v98
	v_fmac_f32_e32 v66, v29, v29
	v_fma_f32 v30, v30, v0, -v18
	v_mul_f32_e32 v18, v47, v98
	v_fmac_f32_e32 v66, v30, v30
	v_fma_f32 v31, v31, v0, -v18
	v_mul_f32_e32 v18, v48, v98
	v_fmac_f32_e32 v66, v31, v31
	v_fma_f32 v32, v32, v0, -v18
	v_mul_f32_e32 v18, v49, v98
	v_fmac_f32_e32 v66, v32, v32
	v_fma_f32 v33, v33, v0, -v18
	v_fmac_f32_e32 v66, v33, v33
	v_mov_b32_e32 v0, v66
	s_nop 1
	v_permlane32_swap_b32_e32 v66, v0
	s_nop 0
	v_add_f32_e32 v0, v66, v0
	v_fmamk_f32 v0, v0, 0x3c800000, v233
	v_cmp_gt_f32_e32 vcc, s2, v0
	v_mul_f32_e32 v18, 0x4f800000, v0
	s_nop 0
	v_cndmask_b32_e32 v0, v0, v18, vcc
	v_sqrt_f32_e32 v18, v0
	s_nop 0
	v_add_u32_e32 v19, -1, v18
	v_fma_f32 v20, -v19, v18, v0
	v_cmp_ge_f32_e64 s[2:3], 0, v20
	v_add_u32_e32 v20, 1, v18
	s_nop 0
	v_cndmask_b32_e64 v19, v18, v19, s[2:3]
	v_fma_f32 v18, -v20, v18, v0
	v_cmp_lt_f32_e64 s[2:3], 0, v18
	s_nop 1
	v_cndmask_b32_e64 v18, v19, v20, s[2:3]
	v_mul_f32_e32 v19, 0x37800000, v18
	v_cndmask_b32_e32 v18, v18, v19, vcc
	v_cmp_class_f32_e32 vcc, v0, v232
	s_nop 1
	v_cndmask_b32_e32 v0, v18, v0, vcc
	v_div_scale_f32 v18, s[2:3], v0, v0, v177
	v_rcp_f32_e32 v19, v18
	v_readlane_b32 s2, v244, 1
	s_add_i32 s2, s2, s68
	v_fma_f32 v20, -v18, v19, 1.0
	v_fmac_f32_e32 v19, v20, v19
	v_div_scale_f32 v20, vcc, v177, v0, v177
	v_mul_f32_e32 v21, v20, v19
	v_fma_f32 v22, -v18, v21, v20
	v_fmac_f32_e32 v21, v22, v19
	v_fma_f32 v18, -v18, v21, v20
	v_div_fmas_f32 v18, v18, v19, v21
	v_div_fixup_f32 v40, v18, v0, v177
	v_or_b32_e32 v0, s2, v185
	v_lshlrev_b64 v[18:19], 11, v[0:1]
	v_lshl_add_u64 v[18:19], s[74:75], 0, v[18:19]
	v_lshl_add_u64 v[18:19], s[76:77], 1, v[18:19]
	v_mul_f32_e32 v0, v50, v40
	v_mul_f32_e32 v20, v51, v40
	v_lshl_add_u64 v[18:19], v[172:173], 1, v[18:19]
	s_mov_b64 s[2:3], 0xb200000
	s_waitcnt vmcnt(18)
	v_mul_f32_e32 v0, v94, v0
	v_mul_f32_e32 v20, v95, v20
	v_lshl_add_u64 v[22:23], v[18:19], 0, s[2:3]
	s_mov_b32 s2, 0xb200000
	v_cvt_pk_bf16_f32 v20, v0, v20
	v_mul_f32_e32 v0, v52, v40
	v_mul_f32_e32 v21, v53, v40
	v_add_co_u32_e32 v18, vcc, s2, v18
	v_mul_f32_e32 v0, v96, v0
	v_mul_f32_e32 v21, v97, v21
	v_addc_co_u32_e32 v19, vcc, 0, v19, vcc
	v_cvt_pk_bf16_f32 v21, v0, v21
	global_store_dwordx2 v[18:19], v[20:21], off
	v_mul_f32_e32 v0, v54, v40
	v_mul_f32_e32 v18, v55, v40
	s_waitcnt vmcnt(18)
	v_mul_f32_e32 v0, v90, v0
	v_mul_f32_e32 v18, v91, v18
	v_cvt_pk_bf16_f32 v18, v0, v18
	v_mul_f32_e32 v0, v56, v40
	v_mul_f32_e32 v19, v57, v40
	v_mul_f32_e32 v0, v92, v0
	v_mul_f32_e32 v19, v93, v19
	v_cvt_pk_bf16_f32 v19, v0, v19
	global_store_dwordx2 v[22:23], v[18:19], off offset:16
	v_mul_f32_e32 v0, v58, v40
	v_mul_f32_e32 v18, v59, v40
	s_waitcnt vmcnt(18)
	v_mul_f32_e32 v0, v86, v0
	v_mul_f32_e32 v18, v87, v18
	v_cvt_pk_bf16_f32 v18, v0, v18
	v_mul_f32_e32 v0, v60, v40
	v_mul_f32_e32 v19, v61, v40
	v_mul_f32_e32 v0, v88, v0
	v_mul_f32_e32 v19, v89, v19
	v_cvt_pk_bf16_f32 v19, v0, v19
	global_store_dwordx2 v[22:23], v[18:19], off offset:32
	v_mul_f32_e32 v0, v62, v40
	v_mul_f32_e32 v18, v63, v40
	s_waitcnt vmcnt(18)
	v_mul_f32_e32 v0, v82, v0
	v_mul_f32_e32 v18, v83, v18
	v_cvt_pk_bf16_f32 v18, v0, v18
	v_mul_f32_e32 v0, v64, v40
	v_mul_f32_e32 v19, v65, v40
	v_mul_f32_e32 v0, v84, v0
	v_mul_f32_e32 v19, v85, v19
	v_cvt_pk_bf16_f32 v19, v0, v19
	v_mul_f32_e32 v0, v34, v40
	s_waitcnt vmcnt(17)
	v_mul_f32_e32 v0, v14, v0
	v_mul_f32_e32 v14, v35, v40
	v_mul_f32_e32 v14, v15, v14
	global_store_dwordx2 v[22:23], v[18:19], off offset:48
	v_cvt_pk_bf16_f32 v14, v0, v14
	v_mul_f32_e32 v0, v36, v40
	v_mul_f32_e32 v15, v37, v40
	v_mul_f32_e32 v0, v16, v0
	v_mul_f32_e32 v15, v17, v15
	v_cvt_pk_bf16_f32 v15, v0, v15
	v_mul_f32_e32 v0, v38, v40
	s_waitcnt vmcnt(17)
	v_mul_f32_e32 v0, v10, v0
	v_mul_f32_e32 v10, v39, v40
	v_mul_f32_e32 v10, v11, v10
	global_store_dwordx2 v[22:23], v[14:15], off offset:64
	v_cvt_pk_bf16_f32 v10, v0, v10
	v_mul_f32_e32 v0, v24, v40
	v_mul_f32_e32 v11, v25, v40
	v_mul_f32_e32 v0, v12, v0
	v_mul_f32_e32 v11, v13, v11
	v_cvt_pk_bf16_f32 v11, v0, v11
	v_mul_f32_e32 v0, v26, v40
	s_waitcnt vmcnt(17)
	v_mul_f32_e32 v0, v6, v0
	v_mul_f32_e32 v6, v27, v40
	v_mul_f32_e32 v6, v7, v6
	global_store_dwordx2 v[22:23], v[10:11], off offset:80
	v_cvt_pk_bf16_f32 v6, v0, v6
	v_mul_f32_e32 v0, v28, v40
	v_mul_f32_e32 v7, v29, v40
	v_mul_f32_e32 v0, v8, v0
	v_mul_f32_e32 v7, v9, v7
	v_cvt_pk_bf16_f32 v7, v0, v7
	v_mul_f32_e32 v0, v30, v40
	s_waitcnt vmcnt(17)
	v_mul_f32_e32 v0, v2, v0
	v_mul_f32_e32 v2, v31, v40
	v_mul_f32_e32 v2, v3, v2
	v_mul_f32_e32 v3, v33, v40
	global_store_dwordx2 v[22:23], v[6:7], off offset:96
	v_cvt_pk_bf16_f32 v2, v0, v2
	v_mul_f32_e32 v0, v32, v40
	v_mul_f32_e32 v3, v5, v3
	v_mul_f32_e32 v0, v4, v0
	v_cvt_pk_bf16_f32 v3, v0, v3
	global_store_dwordx2 v[22:23], v[2:3], off offset:112
	s_mov_b32 s2, s4
	s_mov_b32 s3, s5
	s_mov_b32 s76, s55
	v_mov_b32_e32 v0, v146
	v_mov_b32_e32 v2, v148
	v_mov_b32_e32 v3, v149
	v_mov_b32_e32 v4, v150
	v_mov_b32_e32 v8, v154
	v_mov_b32_e32 v9, v155
	v_mov_b32_e32 v19, v156
	v_mov_b32_e32 v20, v157
	s_mov_b32 s101, 1
	s_waitcnt vmcnt(12)
	s_branch .Lpipe_part2
